# speedup vs baseline: 1.0202x; 1.0071x over previous
; #define MFMA(a, b, c) __builtin_amdgcn_mfma_f32_16x16x32_bf16(a, b, c, 0, 0, 0)
; __device__ __forceinline__ void attn_phase(const Params& p, int layer, char* smem) {
;     ...
;     for (int kt = 0; kt < nkt; ++kt) {
;       if (kt + 1 < nkt) gload(kt + 1);
;       const char* Ks = smem + (kt & 1) * 32768 + mm * 8192;
;       const char* Vs = smem + (kt & 1) * 32768 + 16384;
;       f32x4 st[2][4];
;       __builtin_amdgcn_s_setprio(1);
; #pragma unroll
;       for (int k4 = 0; k4 < 4; ++k4) {
;         const bf16x8 af0 = *(const bf16x8*)(Ks + sw128(k4 * 16 + fr, fq));
;         const bf16x8 af1 = *(const bf16x8*)(Ks + sw128(k4 * 16 + fr, 4 + fq));
;         const f32x4 z4 = {0.f, 0.f, 0.f, 0.f};
;         st[0][k4] = MFMA(af0, qf[0][0], z4);
;         st[1][k4] = MFMA(af0, qf[1][0], z4);
;         st[0][k4] = MFMA(af1, qf[0][1], st[0][k4]);
;         st[1][k4] = MFMA(af1, qf[1][1], st[1][k4]);
;       }
;       __builtin_amdgcn_s_setprio(0);
;       bf16x8 pb[2][2];
; #pragma unroll
;       for (int qt = 0; qt < 2; ++qt) {
;         float ls = 0.f;
; #pragma unroll
;         for (int k4 = 0; k4 < 4; ++k4)
; #pragma unroll
;           for (int j = 0; j < 4; ++j) {
;             float pe = __builtin_amdgcn_exp2f(st[qt][k4][j]);
;             st[qt][k4][j] = pe;
;             ls += pe;
;           }
;         lrun[qt] += ls;
; #pragma unroll
;         for (int k2 = 0; k2 < 2; ++k2) {
;           union { bf16x8 v; unsigned u[4]; } pk;
;           pk.u[0] = pack2(st[qt][k2 * 2][0], st[qt][k2 * 2][1]);
;           pk.u[1] = pack2(st[qt][k2 * 2][2], st[qt][k2 * 2][3]);
;           pk.u[2] = pack2(st[qt][k2 * 2 + 1][0], st[qt][k2 * 2 + 1][1]);
;           pk.u[3] = pack2(st[qt][k2 * 2 + 1][2], st[qt][k2 * 2 + 1][3]);
;           pb[qt][k2] = pk.v;
;         }
;       }
;       __builtin_amdgcn_s_setprio(1);
; #pragma unroll
;       for (int et = 0; et < 8; ++et)
; #pragma unroll
;         for (int k2 = 0; k2 < 2; ++k2) {
;           const bf16x8 av = *(const bf16x8*)(Vs + sw128(et * 16 + fr, k2 * 4 + fq));
;           o[0][et] = MFMA(av, pb[0][k2], o[0][et]);
;           o[1][et] = MFMA(av, pb[1][k2], o[1][et]);
;         }
.LBB0_498:
	s_and_b32 s8, s45, 0x8000
	s_addk_i32 s8, 0x190
	v_add_u32_e32 v169, s8, v159
	s_setprio 1
	v_add_u32_e32 v190, v169, v161
	ds_read_b128 v[170:173], v190
	ds_read_b128 v[174:177], v190 offset:2048
	v_add_u32_e32 v169, v169, v162
	ds_read_b128 v[182:185], v169
	ds_read_b128 v[186:189], v169 offset:2048
	ds_read_b128 v[244:247], v190 offset:4096
	ds_read_b128 v[248:251], v190 offset:6144
	ds_read_b128 v[198:201], v169 offset:4096
	ds_read_b128 v[226:229], v169 offset:6144
	v_lshl_add_u64 v[80:81], v[142:143], 0, v[152:153]
	s_mov_b32 s8, 0x12478000
	v_add_co_u32_e32 v84, vcc, s8, v80
	v_lshl_add_u64 v[92:93], v[142:143], 0, v[150:151]
	s_nop 0
	v_addc_co_u32_e32 v85, vcc, 0, v81, vcc
	s_mov_b32 s8, 0x2d418000
	v_add_co_u32_e32 v88, vcc, s8, v92
	s_mov_b32 s8, 0x2d460000
	s_nop 0
	v_addc_co_u32_e32 v89, vcc, 0, v93, vcc
	v_add_co_u32_e32 v92, vcc, s8, v92
	global_load_dwordx4 v[80:83], v[84:85], off offset:2048
	s_nop 0
	global_load_dwordx4 v[84:87], v[84:85], off offset:2176
	v_addc_co_u32_e32 v93, vcc, 0, v93, vcc
	global_load_dwordx4 v[88:91], v[88:89], off offset:128
	global_load_dwordx4 v[92:95], v[92:93], off offset:128
	s_and_b32 s8, s45, 0x8000
	s_addk_i32 s8, 0x190
	s_waitcnt vmcnt(7) lgkmcnt(7)
	v_mfma_f32_16x16x32_bf16 v[178:181], v[170:173], v[56:59], 0
	s_waitcnt vmcnt(5)
	v_mfma_f32_16x16x32_bf16 v[170:173], v[170:173], v[60:63], 0
	s_waitcnt lgkmcnt(5)
	v_mfma_f32_16x16x32_bf16 v[178:181], v[182:185], v[44:47], v[178:181]
	s_waitcnt vmcnt(4)
	v_mfma_f32_16x16x32_bf16 v[170:173], v[182:185], v[48:51], v[170:173]
	v_mfma_f32_16x16x32_bf16 v[182:185], v[174:177], v[56:59], 0
	v_mfma_f32_16x16x32_bf16 v[174:177], v[174:177], v[60:63], 0
	s_waitcnt lgkmcnt(4)
	v_mfma_f32_16x16x32_bf16 v[182:185], v[186:189], v[44:47], v[182:185]
	v_mfma_f32_16x16x32_bf16 v[174:177], v[186:189], v[48:51], v[174:177]
	s_waitcnt lgkmcnt(3)
	v_mfma_f32_16x16x32_bf16 v[194:197], v[244:247], v[56:59], 0
	v_mfma_f32_16x16x32_bf16 v[186:189], v[244:247], v[60:63], 0
	s_waitcnt lgkmcnt(1)
	v_mfma_f32_16x16x32_bf16 v[194:197], v[198:201], v[44:47], v[194:197]
	v_mfma_f32_16x16x32_bf16 v[186:189], v[198:201], v[48:51], v[186:189]
	v_mfma_f32_16x16x32_bf16 v[198:201], v[248:251], v[56:59], 0
	v_mfma_f32_16x16x32_bf16 v[190:193], v[248:251], v[60:63], 0
	s_waitcnt lgkmcnt(0)
	v_mfma_f32_16x16x32_bf16 v[198:201], v[226:229], v[44:47], v[198:201]
	v_mfma_f32_16x16x32_bf16 v[190:193], v[226:229], v[48:51], v[190:193]
	s_setprio 0
	v_add_u32_e32 v169, s8, v161
	v_add_u32_e32 v252, s8, v162
	ds_read_b128 v[244:247], v169 offset:16384
	ds_read_b128 v[248:251], v169 offset:18432
	v_exp_f32_e32 v227, v178
	v_exp_f32_e32 v226, v170
	v_exp_f32_e32 v179, v179
	v_exp_f32_e32 v178, v171
	v_exp_f32_e32 v229, v180
	v_exp_f32_e32 v228, v172
	v_exp_f32_e32 v181, v181
	v_exp_f32_e32 v180, v173
	v_exp_f32_e32 v231, v182
	v_exp_f32_e32 v230, v174
	v_exp_f32_e32 v182, v175
	v_pk_add_f32 v[174:175], v[226:227], 0 op_sel_hi:[1,0]
	v_exp_f32_e32 v183, v183
	v_pk_add_f32 v[174:175], v[178:179], v[174:175]
	v_exp_f32_e32 v233, v184
	v_pk_add_f32 v[174:175], v[228:229], v[174:175]
	v_exp_f32_e32 v232, v176
	v_exp_f32_e32 v185, v185
	v_pk_add_f32 v[174:175], v[180:181], v[174:175]
	v_exp_f32_e32 v184, v177
	v_exp_f32_e32 v235, v194
	v_pk_add_f32 v[174:175], v[174:175], v[230:231]
	v_exp_f32_e32 v234, v186
	v_exp_f32_e32 v195, v195
	v_pk_add_f32 v[174:175], v[182:183], v[174:175]
	v_exp_f32_e32 v194, v187
	v_exp_f32_e32 v237, v196
	v_exp_f32_e32 v236, v188
	v_pk_add_f32 v[174:175], v[232:233], v[174:175]
	v_exp_f32_e32 v197, v197
	v_exp_f32_e32 v196, v189
	v_pk_add_f32 v[174:175], v[184:185], v[174:175]
	v_exp_f32_e32 v239, v198
	v_exp_f32_e32 v238, v190
	v_pk_add_f32 v[174:175], v[174:175], v[234:235]
	v_exp_f32_e32 v199, v199
	v_exp_f32_e32 v198, v191
	v_pk_add_f32 v[174:175], v[194:195], v[174:175]
	v_exp_f32_e32 v241, v200
	v_exp_f32_e32 v240, v192
	v_pk_add_f32 v[174:175], v[236:237], v[174:175]
	v_exp_f32_e32 v201, v201
	v_exp_f32_e32 v200, v193
	v_pk_add_f32 v[174:175], v[196:197], v[174:175]
	v_cvt_pk_bf16_f32 v170, v227, v179
	v_pk_add_f32 v[174:175], v[174:175], v[238:239]
	v_cvt_pk_bf16_f32 v171, v229, v181
	v_pk_add_f32 v[174:175], v[198:199], v[174:175]
	v_cvt_pk_bf16_f32 v172, v231, v183
	v_pk_add_f32 v[174:175], v[240:241], v[174:175]
	v_cvt_pk_bf16_f32 v173, v233, v185
	v_pk_add_f32 v[186:187], v[200:201], v[174:175]
	v_cvt_pk_bf16_f32 v174, v235, v195
	v_pk_add_f32 v[148:149], v[148:149], v[186:187]
	v_cvt_pk_bf16_f32 v175, v237, v197
	v_cvt_pk_bf16_f32 v176, v239, v199
	v_cvt_pk_bf16_f32 v177, v241, v201
	v_cvt_pk_bf16_f32 v178, v226, v178
	v_cvt_pk_bf16_f32 v179, v228, v180
	v_cvt_pk_bf16_f32 v180, v230, v182
	v_cvt_pk_bf16_f32 v181, v232, v184
	v_cvt_pk_bf16_f32 v182, v234, v194
	v_cvt_pk_bf16_f32 v183, v236, v196
	v_cvt_pk_bf16_f32 v184, v238, v198
	v_cvt_pk_bf16_f32 v185, v240, v200
	s_setprio 1
	ds_read_b128 v[186:189], v169 offset:20480
	s_waitcnt lgkmcnt(2)
	v_mfma_f32_16x16x32_bf16 v[76:79], v[244:247], v[170:173], v[76:79]
	v_mfma_f32_16x16x32_bf16 v[52:55], v[244:247], v[178:181], v[52:55]
	ds_read_b128 v[244:247], v169 offset:22528
	s_waitcnt lgkmcnt(2)
	v_mfma_f32_16x16x32_bf16 v[72:75], v[248:251], v[170:173], v[72:75]
	v_mfma_f32_16x16x32_bf16 v[36:39], v[248:251], v[178:181], v[36:39]
	ds_read_b128 v[248:251], v169 offset:24576
	s_waitcnt lgkmcnt(2)
	v_mfma_f32_16x16x32_bf16 v[68:71], v[186:189], v[170:173], v[68:71]
	v_mfma_f32_16x16x32_bf16 v[28:31], v[186:189], v[178:181], v[28:31]
	ds_read_b128 v[186:189], v169 offset:26624
	s_waitcnt lgkmcnt(2)
; #define MFMA(a, b, c) __builtin_amdgcn_mfma_f32_16x16x32_bf16(a, b, c, 0, 0, 0)
; __device__ __forceinline__ void attn_phase(const Params& p, int layer, char* smem) {
;     ...
;     for (int kt = 0; kt < nkt; ++kt) {
;       if (kt + 1 < nkt) gload(kt + 1);
;       const char* Ks = smem + (kt & 1) * 32768 + mm * 8192;
;       const char* Vs = smem + (kt & 1) * 32768 + 16384;
;       f32x4 st[2][4];
;       __builtin_amdgcn_s_setprio(1);
; #pragma unroll
;       for (int k4 = 0; k4 < 4; ++k4) {
;         const bf16x8 af0 = *(const bf16x8*)(Ks + sw128(k4 * 16 + fr, fq));
;         const bf16x8 af1 = *(const bf16x8*)(Ks + sw128(k4 * 16 + fr, 4 + fq));
;         const f32x4 z4 = {0.f, 0.f, 0.f, 0.f};
;         st[0][k4] = MFMA(af0, qf[0][0], z4);
;         st[1][k4] = MFMA(af0, qf[1][0], z4);
;         st[0][k4] = MFMA(af1, qf[0][1], st[0][k4]);
;         st[1][k4] = MFMA(af1, qf[1][1], st[1][k4]);
;       }
;     ...
;       __builtin_amdgcn_s_setprio(1);
; #pragma unroll
;       for (int et = 0; et < 8; ++et)
; #pragma unroll
;         for (int k2 = 0; k2 < 2; ++k2) {
;           const bf16x8 av = *(const bf16x8*)(Vs + sw128(et * 16 + fr, k2 * 4 + fq));
;           o[0][et] = MFMA(av, pb[0][k2], o[0][et]);
;           o[1][et] = MFMA(av, pb[1][k2], o[1][et]);
;         }
;       __builtin_amdgcn_s_setprio(0);
;       if (kt + 1 < nkt) sstore((kt + 1) & 1);
;       __syncthreads();
	v_mfma_f32_16x16x32_bf16 v[64:67], v[244:247], v[170:173], v[64:67]
	v_mfma_f32_16x16x32_bf16 v[24:27], v[244:247], v[178:181], v[24:27]
	ds_read_b128 v[244:247], v169 offset:28672
	s_waitcnt lgkmcnt(2)
	v_mfma_f32_16x16x32_bf16 v[40:43], v[248:251], v[170:173], v[40:43]
	v_mfma_f32_16x16x32_bf16 v[20:23], v[248:251], v[178:181], v[20:23]
	ds_read_b128 v[248:251], v169 offset:30720
	s_waitcnt lgkmcnt(2)
	v_mfma_f32_16x16x32_bf16 v[32:35], v[186:189], v[170:173], v[32:35]
	v_mfma_f32_16x16x32_bf16 v[16:19], v[186:189], v[178:181], v[16:19]
	ds_read_b128 v[186:189], v252 offset:16384
	s_waitcnt lgkmcnt(2)
	v_mfma_f32_16x16x32_bf16 v[12:15], v[244:247], v[170:173], v[12:15]
	v_mfma_f32_16x16x32_bf16 v[4:7], v[244:247], v[178:181], v[4:7]
	ds_read_b128 v[244:247], v252 offset:18432
	s_waitcnt lgkmcnt(2)
	v_mfma_f32_16x16x32_bf16 v[8:11], v[248:251], v[170:173], v[8:11]
	v_mfma_f32_16x16x32_bf16 v[0:3], v[248:251], v[178:181], v[0:3]
	ds_read_b128 v[248:251], v252 offset:20480
	s_waitcnt lgkmcnt(2)
	v_mfma_f32_16x16x32_bf16 v[76:79], v[186:189], v[174:177], v[76:79]
	v_mfma_f32_16x16x32_bf16 v[52:55], v[186:189], v[182:185], v[52:55]
	ds_read_b128 v[186:189], v252 offset:22528
	s_waitcnt lgkmcnt(2)
	v_mfma_f32_16x16x32_bf16 v[72:75], v[244:247], v[174:177], v[72:75]
	v_mfma_f32_16x16x32_bf16 v[36:39], v[244:247], v[182:185], v[36:39]
	ds_read_b128 v[244:247], v252 offset:24576
	s_waitcnt lgkmcnt(2)
	v_mfma_f32_16x16x32_bf16 v[68:71], v[248:251], v[174:177], v[68:71]
	v_mfma_f32_16x16x32_bf16 v[28:31], v[248:251], v[182:185], v[28:31]
	ds_read_b128 v[248:251], v252 offset:26624
	s_waitcnt lgkmcnt(2)
	v_mfma_f32_16x16x32_bf16 v[64:67], v[186:189], v[174:177], v[64:67]
	v_mfma_f32_16x16x32_bf16 v[24:27], v[186:189], v[182:185], v[24:27]
	ds_read_b128 v[186:189], v252 offset:28672
	s_waitcnt lgkmcnt(2)
	v_mfma_f32_16x16x32_bf16 v[40:43], v[244:247], v[174:177], v[40:43]
	v_mfma_f32_16x16x32_bf16 v[20:23], v[244:247], v[182:185], v[20:23]
	ds_read_b128 v[244:247], v252 offset:30720
	s_waitcnt lgkmcnt(2)
	v_mfma_f32_16x16x32_bf16 v[32:35], v[248:251], v[174:177], v[32:35]
	v_mfma_f32_16x16x32_bf16 v[16:19], v[248:251], v[182:185], v[16:19]
	s_waitcnt lgkmcnt(1)
	v_mfma_f32_16x16x32_bf16 v[12:15], v[186:189], v[174:177], v[12:15]
	v_mfma_f32_16x16x32_bf16 v[4:7], v[186:189], v[182:185], v[4:7]
	s_waitcnt lgkmcnt(0)
	v_mfma_f32_16x16x32_bf16 v[8:11], v[244:247], v[174:177], v[8:11]
	v_mfma_f32_16x16x32_bf16 v[0:3], v[244:247], v[182:185], v[0:3]
	s_setprio 0
	s_add_i32 s45, s45, 0x8000
	s_and_b32 s8, s45, 0x8000
	s_addk_i32 s8, 0x190
	v_add_u32_e32 v169, s8, v155
	s_mov_b64 s[46:47], 0x60000
	s_waitcnt vmcnt(3)
	ds_write_b128 v169, v[80:83]
	s_waitcnt vmcnt(2)
	ds_write_b128 v169, v[84:87] offset:8192
	v_add3_u32 v80, s8, v157, v156
	v_add3_u32 v81, s8, v158, v156
	v_lshl_add_u64 v[150:151], v[150:151], 0, s[48:49]
	s_cmp_lg_u32 s26, s45
	v_lshl_add_u64 v[152:153], v[152:153], 0, s[46:47]
	s_waitcnt vmcnt(1)
	ds_write_b64 v80, v[88:89] offset:16384
	ds_write_b64 v81, v[90:91] offset:16384
	s_waitcnt vmcnt(0)
	ds_write_b64 v80, v[92:93] offset:24576
	ds_write_b64 v81, v[94:95] offset:24576
	s_waitcnt lgkmcnt(0)
	s_barrier
	s_cbranch_scc1 .LBB0_498
	v_add_u32_e32 v88, s8, v159
	s_setprio 1
	v_add_u32_e32 v169, v88, v161
	ds_read_b128 v[80:83], v169
	v_add_u32_e32 v178, v88, v162
	ds_read_b128 v[88:91], v178
	s_waitcnt lgkmcnt(1)
	v_mfma_f32_16x16x32_bf16 v[84:87], v[80:83], v[56:59], 0
	ds_read_b128 v[150:153], v178 offset:2048
	ds_read_b128 v[174:177], v178 offset:4096
	v_mfma_f32_16x16x32_bf16 v[80:83], v[80:83], v[60:63], 0
	s_waitcnt lgkmcnt(2)
	v_mfma_f32_16x16x32_bf16 v[84:87], v[88:91], v[44:47], v[84:87]
	v_mfma_f32_16x16x32_bf16 v[80:83], v[88:91], v[48:51], v[80:83]
	ds_read_b128 v[88:91], v169 offset:2048
	s_waitcnt lgkmcnt(0)
	v_mfma_f32_16x16x32_bf16 v[92:95], v[88:91], v[56:59], 0
	v_mfma_f32_16x16x32_bf16 v[88:91], v[88:91], v[60:63], 0
	v_mfma_f32_16x16x32_bf16 v[92:95], v[150:153], v[44:47], v[92:95]
	v_mfma_f32_16x16x32_bf16 v[88:91], v[150:153], v[48:51], v[88:91]
	ds_read_b128 v[150:153], v169 offset:4096
	s_waitcnt lgkmcnt(0)
	v_mfma_f32_16x16x32_bf16 v[170:173], v[150:153], v[56:59], 0
	v_mfma_f32_16x16x32_bf16 v[150:153], v[150:153], v[60:63], 0
	v_mfma_f32_16x16x32_bf16 v[170:173], v[174:177], v[44:47], v[170:173]
	v_mfma_f32_16x16x32_bf16 v[150:153], v[174:177], v[48:51], v[150:153]
	ds_read_b128 v[174:177], v169 offset:6144
	s_waitcnt lgkmcnt(0)
	v_mfma_f32_16x16x32_bf16 v[56:59], v[174:177], v[56:59], 0
	v_mfma_f32_16x16x32_bf16 v[60:63], v[174:177], v[60:63], 0
	ds_read_b128 v[174:177], v178 offset:6144
	s_waitcnt lgkmcnt(0)
; #define MFMA(a, b, c) __builtin_amdgcn_mfma_f32_16x16x32_bf16(a, b, c, 0, 0, 0)
; __device__ __forceinline__ void attn_phase(const Params& p, int layer, char* smem) {
;     ...
;       bf16x8 pb[2][2];
; #pragma unroll
;       for (int qt = 0; qt < 2; ++qt) {
;         float ls = 0.f;
; #pragma unroll
;         for (int k4 = 0; k4 < 4; ++k4)
; #pragma unroll
;           for (int j = 0; j < 4; ++j) {
;             float pe = __builtin_amdgcn_exp2f(st[qt][k4][j]);
;             st[qt][k4][j] = pe;
;             ls += pe;
;           }
;         lrun[qt] += ls;
; #pragma unroll
;         for (int k2 = 0; k2 < 2; ++k2) {
;           union { bf16x8 v; unsigned u[4]; } pk;
;           pk.u[0] = pack2(st[qt][k2 * 2][0], st[qt][k2 * 2][1]);
;           pk.u[1] = pack2(st[qt][k2 * 2][2], st[qt][k2 * 2][3]);
;           pk.u[2] = pack2(st[qt][k2 * 2 + 1][0], st[qt][k2 * 2 + 1][1]);
;           pk.u[3] = pack2(st[qt][k2 * 2 + 1][2], st[qt][k2 * 2 + 1][3]);
;           pb[qt][k2] = pk.v;
;         }
;       }
;       __builtin_amdgcn_s_setprio(1);
; #pragma unroll
;       for (int et = 0; et < 8; ++et)
; #pragma unroll
;         for (int k2 = 0; k2 < 2; ++k2) {
;           const bf16x8 av = *(const bf16x8*)(Vs + sw128(et * 16 + fr, k2 * 4 + fq));
;           o[0][et] = MFMA(av, pb[0][k2], o[0][et]);
;           o[1][et] = MFMA(av, pb[1][k2], o[1][et]);
;         }
;       __builtin_amdgcn_s_setprio(0);
;       if (kt + 1 < nkt) sstore((kt + 1) & 1);
;       __syncthreads();
;     }
; #pragma unroll
;     for (int qt = 0; qt < 2; ++qt) {
;       float lt = lrun[qt];
;       lt += __shfl_xor(lt, 16);
	v_mfma_f32_16x16x32_bf16 v[44:47], v[174:177], v[44:47], v[56:59]
	v_mfma_f32_16x16x32_bf16 v[60:63], v[174:177], v[48:51], v[60:63]
	s_setprio 0
	v_exp_f32_e32 v48, v84
	v_exp_f32_e32 v49, v85
	v_exp_f32_e32 v50, v86
	v_exp_f32_e32 v51, v87
	v_add_f32_e32 v56, 0, v48
	v_exp_f32_e32 v58, v92
	v_add_f32_e32 v56, v49, v56
	v_exp_f32_e32 v59, v93
	v_add_f32_e32 v56, v50, v56
	v_exp_f32_e32 v84, v94
	v_add_f32_e32 v56, v51, v56
	v_exp_f32_e32 v85, v95
	v_add_f32_e32 v56, v56, v58
	v_exp_f32_e32 v86, v170
	v_add_f32_e32 v56, v59, v56
	v_exp_f32_e32 v87, v171
	v_add_f32_e32 v56, v84, v56
	v_exp_f32_e32 v92, v172
	v_add_f32_e32 v56, v85, v56
	v_exp_f32_e32 v93, v173
	v_add_f32_e32 v56, v56, v86
	v_exp_f32_e32 v44, v44
	v_exp_f32_e32 v45, v45
	v_add_f32_e32 v56, v87, v56
	v_add_f32_e32 v56, v92, v56
	v_exp_f32_e32 v46, v46
	v_exp_f32_e32 v47, v47
	v_add_f32_e32 v56, v93, v56
	v_add_f32_e32 v56, v56, v44
	v_cvt_pk_bf16_f32 v57, v50, v51
	v_cvt_pk_bf16_f32 v50, v44, v45
	v_exp_f32_e32 v44, v80
	v_add_f32_e32 v56, v45, v56
	v_exp_f32_e32 v45, v81
	v_add_f32_e32 v56, v46, v56
	v_cvt_pk_bf16_f32 v51, v46, v47
	v_exp_f32_e32 v46, v82
	v_add_f32_e32 v56, v47, v56
	v_exp_f32_e32 v47, v83
	v_add_f32_e32 v80, 0, v44
	v_exp_f32_e32 v81, v88
	v_add_f32_e32 v80, v45, v80
	v_exp_f32_e32 v82, v89
	v_add_f32_e32 v80, v46, v80
	v_exp_f32_e32 v83, v90
	v_cvt_pk_bf16_f32 v58, v58, v59
	v_cvt_pk_bf16_f32 v59, v84, v85
	v_add_f32_e32 v80, v47, v80
	v_exp_f32_e32 v84, v91
	v_add_f32_e32 v80, v80, v81
	v_exp_f32_e32 v85, v150
	v_add_f32_e32 v169, v149, v56
	v_cvt_pk_bf16_f32 v56, v48, v49
	v_cvt_pk_bf16_f32 v48, v86, v87
	v_add_f32_e32 v80, v82, v80
	v_exp_f32_e32 v86, v151
	v_add_f32_e32 v80, v83, v80
	v_exp_f32_e32 v87, v152
	v_add_f32_e32 v80, v84, v80
	v_exp_f32_e32 v88, v153
	v_add_f32_e32 v80, v80, v85
	v_exp_f32_e32 v89, v60
	v_add_f32_e32 v80, v86, v80
	v_exp_f32_e32 v90, v61
	v_add_f32_e32 v80, v87, v80
	v_exp_f32_e32 v91, v62
	v_cvt_pk_bf16_f32 v49, v92, v93
	v_add_f32_e32 v80, v88, v80
	v_exp_f32_e32 v92, v63
	v_add_f32_e32 v60, v80, v89
	v_add_f32_e32 v60, v90, v60
	v_add_f32_e32 v60, v91, v60
	v_add_f32_e32 v60, v92, v60
	v_add_f32_e32 v152, v148, v60
	v_cvt_pk_bf16_f32 v60, v44, v45
	v_cvt_pk_bf16_f32 v61, v46, v47
	v_cvt_pk_bf16_f32 v62, v81, v82
	v_cvt_pk_bf16_f32 v63, v83, v84
	v_cvt_pk_bf16_f32 v80, v85, v86
	v_cvt_pk_bf16_f32 v81, v87, v88
	v_cvt_pk_bf16_f32 v82, v89, v90
	v_cvt_pk_bf16_f32 v83, v91, v92
	s_setprio 1
	v_add_u32_e32 v153, s8, v161
	ds_read_b128 v[44:47], v153 offset:16384
	v_add_u32_e32 v170, s8, v162
	s_waitcnt lgkmcnt(0)
	v_mfma_f32_16x16x32_bf16 v[76:79], v[44:47], v[56:59], v[76:79]
	v_mfma_f32_16x16x32_bf16 v[44:47], v[44:47], v[60:63], v[52:55]
	s_nop 2
	ds_read_b128 v[52:55], v170 offset:16384
	s_waitcnt lgkmcnt(0)
	v_mfma_f32_16x16x32_bf16 v[76:79], v[52:55], v[48:51], v[76:79]
	v_mfma_f32_16x16x32_bf16 v[44:47], v[52:55], v[80:83], v[44:47]
	ds_read_b128 v[52:55], v153 offset:18432
	s_waitcnt lgkmcnt(0)
	v_mfma_f32_16x16x32_bf16 v[72:75], v[52:55], v[56:59], v[72:75]
	v_mfma_f32_16x16x32_bf16 v[36:39], v[52:55], v[60:63], v[36:39]
	ds_read_b128 v[52:55], v170 offset:18432
	s_waitcnt lgkmcnt(0)
	v_mfma_f32_16x16x32_bf16 v[72:75], v[52:55], v[48:51], v[72:75]
	v_mfma_f32_16x16x32_bf16 v[36:39], v[52:55], v[80:83], v[36:39]
	ds_read_b128 v[52:55], v153 offset:20480
	s_waitcnt lgkmcnt(0)
	v_mfma_f32_16x16x32_bf16 v[68:71], v[52:55], v[56:59], v[68:71]
	v_mfma_f32_16x16x32_bf16 v[28:31], v[52:55], v[60:63], v[28:31]
	ds_read_b128 v[52:55], v170 offset:20480
	s_waitcnt lgkmcnt(0)
	v_mfma_f32_16x16x32_bf16 v[68:71], v[52:55], v[48:51], v[68:71]
	v_mfma_f32_16x16x32_bf16 v[52:55], v[52:55], v[80:83], v[28:31]
	s_nop 3
	ds_read_b128 v[28:31], v153 offset:22528
	s_waitcnt lgkmcnt(0)
	v_mfma_f32_16x16x32_bf16 v[64:67], v[28:31], v[56:59], v[64:67]
	v_mfma_f32_16x16x32_bf16 v[24:27], v[28:31], v[60:63], v[24:27]
	ds_read_b128 v[28:31], v170 offset:22528
	s_waitcnt lgkmcnt(0)
	v_mfma_f32_16x16x32_bf16 v[84:87], v[28:31], v[80:83], v[24:27]
	s_nop 4
	ds_read_b128 v[24:27], v153 offset:24576
	v_mfma_f32_16x16x32_bf16 v[64:67], v[28:31], v[48:51], v[64:67]
	s_waitcnt lgkmcnt(0)
	v_mfma_f32_16x16x32_bf16 v[28:31], v[24:27], v[56:59], v[40:43]
	v_mfma_f32_16x16x32_bf16 v[20:23], v[24:27], v[60:63], v[20:23]
	ds_read_b128 v[24:27], v170 offset:24576
	s_waitcnt lgkmcnt(0)
	v_mfma_f32_16x16x32_bf16 v[88:91], v[24:27], v[80:83], v[20:23]
	s_nop 4
	ds_read_b128 v[20:23], v153 offset:26624
	v_mfma_f32_16x16x32_bf16 v[40:43], v[24:27], v[48:51], v[28:31]
	s_waitcnt lgkmcnt(0)
	v_mfma_f32_16x16x32_bf16 v[24:27], v[20:23], v[56:59], v[32:35]
	v_mfma_f32_16x16x32_bf16 v[16:19], v[20:23], v[60:63], v[16:19]
	ds_read_b128 v[20:23], v170 offset:26624
	s_waitcnt lgkmcnt(0)
	v_mfma_f32_16x16x32_bf16 v[92:95], v[20:23], v[80:83], v[16:19]
	s_nop 4
	ds_read_b128 v[16:19], v153 offset:28672
	s_waitcnt lgkmcnt(0)
	v_mfma_f32_16x16x32_bf16 v[12:15], v[16:19], v[56:59], v[12:15]
	v_mfma_f32_16x16x32_bf16 v[4:7], v[16:19], v[60:63], v[4:7]
	ds_read_b128 v[16:19], v170 offset:28672
	s_waitcnt lgkmcnt(0)
	v_mfma_f32_16x16x32_bf16 v[148:151], v[16:19], v[80:83], v[4:7]
	s_nop 4
	ds_read_b128 v[4:7], v153 offset:30720
	s_waitcnt lgkmcnt(0)
	v_mfma_f32_16x16x32_bf16 v[8:11], v[4:7], v[56:59], v[8:11]
	v_mfma_f32_16x16x32_bf16 v[0:3], v[4:7], v[60:63], v[0:3]
	ds_read_b128 v[4:7], v170 offset:30720
	v_mfma_f32_16x16x32_bf16 v[32:35], v[20:23], v[48:51], v[24:27]
	v_mfma_f32_16x16x32_bf16 v[12:15], v[16:19], v[48:51], v[12:15]
	s_waitcnt lgkmcnt(0)
	v_mfma_f32_16x16x32_bf16 v[8:11], v[4:7], v[48:51], v[8:11]
	v_mfma_f32_16x16x32_bf16 v[80:83], v[4:7], v[80:83], v[0:3]
	s_setprio 0
	s_nop 1
	ds_bpermute_b32 v0, v104, v169
	s_waitcnt lgkmcnt(0)
	s_barrier
; __device__ __forceinline__ void attn_phase(const Params& p, int layer, char* smem) {
;     ...
; #pragma unroll
;     for (int qt = 0; qt < 2; ++qt) {
;       float lt = lrun[qt];
;       lt += __shfl_xor(lt, 16);
;       lt += __shfl_xor(lt, 32);
;       float inv = 1.f / lt;
; #pragma unroll
;       for (int et = 0; et < 8; ++et) {
;         o[qt][et][0] *= inv; o[qt][et][1] *= inv; o[qt][et][2] *= inv; o[qt][et][3] *= inv;
;       }
;     }
;     if (mm == 1) {
; #pragma unroll
;       for (int qt = 0; qt < 2; ++qt)
; #pragma unroll
;         for (int et = 0; et < 8; ++et) {
;           int q = wq * 32 + qt * 16 + fr;
;           *(float4*)(comb + q * 128 + et * 16 + fq * 4) = float4{o[qt][et][0], o[qt][et][1], o[qt][et][2], o[qt][et][3]};
;         }
	v_add_f32_e32 v0, v169, v0
	ds_bpermute_b32 v1, v121, v0
	s_waitcnt lgkmcnt(0)
	v_add_f32_e32 v0, v0, v1
	v_div_scale_f32 v1, s[8:9], v0, v0, 1.0
	v_rcp_f32_e32 v2, v1
	v_div_scale_f32 v3, vcc, 1.0, v0, 1.0
	v_fma_f32 v4, -v1, v2, 1.0
	v_fmac_f32_e32 v2, v4, v2
	v_mul_f32_e32 v4, v3, v2
	v_fma_f32 v5, -v1, v4, v3
	v_fmac_f32_e32 v4, v5, v2
	v_fma_f32 v1, -v1, v4, v3
	v_div_fmas_f32 v1, v1, v2, v4
	v_div_fixup_f32 v0, v1, v0, 1.0
	v_mov_b32_e32 v2, v40
	v_mov_b32_e32 v3, v32
	v_pk_mul_f32 v[60:61], v[2:3], v[0:1] op_sel_hi:[1,0]
	v_mov_b32_e32 v32, v41
	v_mov_b32_e32 v2, v42
	v_mov_b32_e32 v3, v34
	v_pk_mul_f32 v[28:29], v[76:77], v[0:1] op_sel_hi:[1,0]
	v_pk_mul_f32 v[30:31], v[78:79], v[0:1] op_sel_hi:[1,0]
	v_pk_mul_f32 v[24:25], v[72:73], v[0:1] op_sel_hi:[1,0]
	v_pk_mul_f32 v[26:27], v[74:75], v[0:1] op_sel_hi:[1,0]
	v_pk_mul_f32 v[20:21], v[68:69], v[0:1] op_sel_hi:[1,0]
	v_pk_mul_f32 v[22:23], v[70:71], v[0:1] op_sel_hi:[1,0]
	v_pk_mul_f32 v[16:17], v[64:65], v[0:1] op_sel_hi:[1,0]
	v_pk_mul_f32 v[18:19], v[66:67], v[0:1] op_sel_hi:[1,0]
	v_pk_mul_f32 v[62:63], v[32:33], v[0:1] op_sel_hi:[1,0]
	v_pk_mul_f32 v[64:65], v[2:3], v[0:1] op_sel_hi:[1,0]
	ds_bpermute_b32 v1, v104, v152
	v_mov_b32_e32 v34, v43
	v_mov_b32_e32 v2, v12
	v_mov_b32_e32 v3, v8
	v_mov_b32_e32 v8, v13
	s_waitcnt lgkmcnt(0)
	v_pk_mul_f32 v[66:67], v[34:35], v[0:1] op_sel_hi:[1,0]
	v_pk_mul_f32 v[48:49], v[2:3], v[0:1] op_sel_hi:[1,0]
	v_add_f32_e32 v1, v152, v1
	ds_bpermute_b32 v4, v121, v1
	v_pk_mul_f32 v[50:51], v[8:9], v[0:1] op_sel_hi:[1,0]
	v_mov_b32_e32 v2, v14
	v_mov_b32_e32 v3, v10
	v_mov_b32_e32 v10, v15
	s_waitcnt lgkmcnt(0)
	v_add_f32_e32 v1, v1, v4
	v_div_scale_f32 v4, s[8:9], v1, v1, 1.0
	v_rcp_f32_e32 v5, v4
	v_pk_mul_f32 v[56:57], v[2:3], v[0:1] op_sel_hi:[1,0]
	v_pk_mul_f32 v[58:59], v[10:11], v[0:1] op_sel_hi:[1,0]
	v_mov_b32_e32 v32, v88
	v_fma_f32 v0, -v4, v5, 1.0
	v_fmac_f32_e32 v5, v0, v5
	v_div_scale_f32 v0, vcc, 1.0, v1, 1.0
	v_mul_f32_e32 v2, v0, v5
	v_fma_f32 v3, -v4, v2, v0
	v_fmac_f32_e32 v2, v3, v5
	v_fma_f32 v0, -v4, v2, v0
	v_div_fmas_f32 v0, v0, v5, v2
	v_div_fixup_f32 v68, v0, v1, 1.0
	v_pk_mul_f32 v[0:1], v[44:45], v[68:69] op_sel_hi:[1,0]
	v_pk_mul_f32 v[4:5], v[36:37], v[68:69] op_sel_hi:[1,0]
	v_mov_b32_e32 v33, v92
	v_mov_b32_e32 v92, v89
	v_mov_b32_e32 v36, v90
	v_mov_b32_e32 v37, v94
	v_mov_b32_e32 v94, v91
	v_mov_b32_e32 v40, v148
	v_mov_b32_e32 v41, v80
	v_mov_b32_e32 v80, v149
	v_mov_b32_e32 v44, v150
	v_mov_b32_e32 v45, v82
	v_mov_b32_e32 v82, v151
	v_pk_mul_f32 v[2:3], v[46:47], v[68:69] op_sel_hi:[1,0]
	v_pk_mul_f32 v[6:7], v[38:39], v[68:69] op_sel_hi:[1,0]
	v_pk_mul_f32 v[12:13], v[52:53], v[68:69] op_sel_hi:[1,0]
	v_pk_mul_f32 v[14:15], v[54:55], v[68:69] op_sel_hi:[1,0]
	v_pk_mul_f32 v[8:9], v[84:85], v[68:69] op_sel_hi:[1,0]
	v_pk_mul_f32 v[10:11], v[86:87], v[68:69] op_sel_hi:[1,0]
	v_pk_mul_f32 v[32:33], v[32:33], v[68:69] op_sel_hi:[1,0]
	v_pk_mul_f32 v[34:35], v[92:93], v[68:69] op_sel_hi:[1,0]
	v_pk_mul_f32 v[36:37], v[36:37], v[68:69] op_sel_hi:[1,0]
	v_pk_mul_f32 v[38:39], v[94:95], v[68:69] op_sel_hi:[1,0]
	v_pk_mul_f32 v[40:41], v[40:41], v[68:69] op_sel_hi:[1,0]
	v_pk_mul_f32 v[42:43], v[80:81], v[68:69] op_sel_hi:[1,0]
	v_pk_mul_f32 v[44:45], v[44:45], v[68:69] op_sel_hi:[1,0]
	v_pk_mul_f32 v[46:47], v[82:83], v[68:69] op_sel_hi:[1,0]
	s_and_saveexec_b64 s[8:9], s[0:1]
	s_cbranch_execz .LBB0_501
	v_mov_b32_e32 v52, v60
	v_mov_b32_e32 v53, v62
	v_mov_b32_e32 v54, v64
	v_mov_b32_e32 v55, v66
	ds_write_b128 v163, v[28:31]
	ds_write_b128 v163, v[24:27] offset:64
	ds_write_b128 v163, v[20:23] offset:128
	ds_write_b128 v163, v[16:19] offset:192
	ds_write_b128 v163, v[52:55] offset:256
	v_mov_b32_e32 v52, v61
	v_mov_b32_e32 v53, v63
	v_mov_b32_e32 v54, v65
	v_mov_b32_e32 v55, v67
	ds_write_b128 v163, v[52:55] offset:320
	v_mov_b32_e32 v52, v48
	v_mov_b32_e32 v53, v50
	v_mov_b32_e32 v54, v56
	v_mov_b32_e32 v55, v58
	ds_write_b128 v163, v[52:55] offset:384
	v_mov_b32_e32 v52, v49
	v_mov_b32_e32 v53, v51
	v_mov_b32_e32 v54, v57
	v_mov_b32_e32 v55, v59
	ds_write_b128 v163, v[52:55] offset:448
	ds_write_b128 v163, v[0:3] offset:8192
	ds_write_b128 v163, v[4:7] offset:8256
	ds_write_b128 v163, v[12:15] offset:8320
	ds_write_b128 v163, v[8:11] offset:8384
	v_mov_b32_e32 v52, v32
	v_mov_b32_e32 v53, v34
	v_mov_b32_e32 v54, v36
	v_mov_b32_e32 v55, v38
	ds_write_b128 v163, v[52:55] offset:8448
	v_mov_b32_e32 v52, v33
	v_mov_b32_e32 v53, v35
	v_mov_b32_e32 v54, v37
	v_mov_b32_e32 v55, v39
	ds_write_b128 v163, v[52:55] offset:8512
	v_mov_b32_e32 v52, v40
	v_mov_b32_e32 v53, v42
	v_mov_b32_e32 v54, v44
	v_mov_b32_e32 v55, v46
	ds_write_b128 v163, v[52:55] offset:8576
	v_mov_b32_e32 v52, v41
	v_mov_b32_e32 v53, v43
	v_mov_b32_e32 v54, v45
	v_mov_b32_e32 v55, v47
	ds_write_b128 v163, v[52:55] offset:8640
